# queue renumbered: weight copies follow the decode items and are taken before the 3->4 barrier is released
# baseline (speedup 1.0000x reference)
.LBB0_517:
	s_or_b64 exec, exec, s[0:1]
	s_waitcnt lgkmcnt(0)
	s_barrier
	ds_read_b32 v1, v232
	s_mov_b64 s[0:1], -1
	s_waitcnt lgkmcnt(0)
	s_barrier
	v_readfirstlane_b32 s60, v1
	s_cmpk_lt_i32 s60, 0x80
	s_cbranch_scc1 .Lp3d_go
	s_cmpk_gt_i32 s60, 0x58f
	s_cbranch_scc1 .Lp3d_chk
	s_cmpk_lt_i32 s60, 0x170
	s_cbranch_scc0 .Lp3d_sub
	s_addk_i32 s60, 0x420
	s_branch .Lp3d_go
.Lp3d_sub:
	s_addk_i32 s60, 0xff10
.Lp3d_chk:
	v_mov_b32_e32 v2, 0x24200
	ds_read_b32 v1, v2
	s_waitcnt lgkmcnt(0)
	v_readfirstlane_b32 s6, v1
	s_cmp_eq_u32 s6, 0
	s_cbranch_scc1 .Lp3d_go
	s_barrier
	s_and_saveexec_b64 s[2:3], s[94:95]
	s_cbranch_execz .Lp3d_wd
	ds_read_b32 v1, v2 offset:8
	s_waitcnt lgkmcnt(0)
	v_readfirstlane_b32 s10, v1
	ds_read_b32 v1, v2 offset:12
	s_waitcnt lgkmcnt(0)
	v_readfirstlane_b32 s11, v1
	ds_read_b32 v1, v2 offset:4
	s_waitcnt lgkmcnt(0)
	ds_write_b32 v2, v3
	s_mov_b32 s6, 0
	s_nop 4
